# seam-latency trims on v63: LayerNorm gain/bias LDS staging completed under the row loads (prologue de-serialisation) + group-barrier invalidate issued at arrival
# speedup vs baseline: 1.0037x; 1.0037x over previous
.Lmy_lnmap_a:
	s_lshl_b32 s2, s99, 3
	s_add_i32 s2, s0, s2
	s_mov_b64 s[12:13], s[96:97]
	s_mov_b64 s[16:17], s[96:97]
	s_mov_b64 s[20:21], s[96:97]
	s_mov_b64 s[18:19], s[96:97]
	s_cmpk_gt_i32 s2, 0x7ff
	s_cbranch_scc1 .LBB0_1978
	s_load_dwordx2 s[20:21], s[20:21], 0x110
	s_nop 0
	s_load_dwordx2 s[8:9], s[8:9], 0x110
	s_nop 0
	s_load_dwordx2 s[22:23], s[12:13], 0x10
	s_nop 0
	s_load_dwordx2 s[16:17], s[16:17], 0x18
	s_nop 0
	s_load_dwordx2 s[18:19], s[18:19], 0x110
	s_waitcnt lgkmcnt(0)
	s_add_u32 s12, s20, 0x900000
	s_addc_u32 s13, s21, 0
	s_lshl_b32 s10, s48, 12
	s_lshl_b64 s[26:27], s[10:11], 2
	s_add_u32 s16, s16, s26
	s_addc_u32 s17, s17, s27
	s_add_u32 s22, s22, s26
	s_addc_u32 s23, s23, s27
	s_lshl_b32 s36, s2, 3
	v_lshlrev_b32_e32 v2, 3, v0
	s_cmp_lg_u64 s[20:21], 0
	v_ashrrev_i32_e32 v3, 31, v2
	s_cselect_b64 s[2:3], -1, 0
	v_cmp_eq_u32_e32 vcc, 0, v0
	v_lshlrev_b64 v[4:5], 2, v[2:3]
	s_and_b64 s[42:43], vcc, s[2:3]
	s_lshl_b32 s98, s80, 10
	v_lshl_add_u32 v194, v0, 4, s98
	global_load_dwordx4 v[196:199], v194, s[22:23]
	global_load_dwordx4 v[200:203], v194, s[16:17]
	v_lshlrev_b32_e32 v195, 5, v0
	v_lshl_add_u64 v[116:117], s[22:23], 0, v[4:5]
	v_lshl_add_u64 v[118:119], s[16:17], 0, v[4:5]
	s_mov_b64 s[2:3], 0x1000
	v_ashrrev_i32_e32 v1, 31, v0
	v_lshl_add_u64 v[120:121], v[116:117], 0, s[2:3]
	v_lshl_add_u64 v[122:123], v[118:119], 0, s[2:3]
	s_mov_b64 s[2:3], 0x1800
	s_lshl_b32 s0, s0, 4
	s_ashr_i32 s37, s36, 31
	v_lshl_add_u64 v[124:125], v[116:117], 0, s[2:3]
	v_lshl_add_u64 v[126:127], v[118:119], 0, s[2:3]
	s_lshl_b32 s44, s99, 7
	s_add_i32 s44, s44, s0
	s_lshl_b64 s[46:47], s[36:37], 12
	v_lshl_add_u64 v[128:129], v[2:3], 1, s[18:19]
	v_lshl_add_u64 v[130:131], v[0:1], 4, s[8:9]
	s_branch .LBB0_1962

.LBB0_1962:
	s_nop 0
	v_lshl_add_u64 v[0:1], v[130:131], 0, s[46:47]
	v_add_co_u32_e32 v2, vcc, 0x12b00000, v0
	s_nop 1
	v_addc_co_u32_e32 v3, vcc, 0, v1, vcc
	global_load_dwordx4 v[132:135], v[2:3], off
	global_load_dwordx4 v[136:139], v[2:3], off offset:1024
	global_load_dwordx4 v[140:143], v[2:3], off offset:2048
	global_load_dwordx4 v[112:115], v[2:3], off offset:3072
	v_add_co_u32_e32 v4, vcc, 0x12b01000, v0
	s_nop 1
	v_addc_co_u32_e32 v5, vcc, 0, v1, vcc
	v_add_co_u32_e32 v2, vcc, 0x12b02000, v0
	s_nop 1
	v_addc_co_u32_e32 v3, vcc, 0, v1, vcc
	global_load_dwordx4 v[108:111], v[4:5], off
	global_load_dwordx4 v[104:107], v[4:5], off offset:1024
	global_load_dwordx4 v[100:103], v[4:5], off offset:2048
	global_load_dwordx4 v[96:99], v[4:5], off offset:3072
	v_add_co_u32_e32 v4, vcc, 0x12b03000, v0
	s_nop 1
	v_addc_co_u32_e32 v5, vcc, 0, v1, vcc
	global_load_dwordx4 v[92:95], v[2:3], off
	global_load_dwordx4 v[88:91], v[2:3], off offset:1024
	global_load_dwordx4 v[84:87], v[2:3], off offset:2048
	global_load_dwordx4 v[80:83], v[2:3], off offset:3072
	v_add_co_u32_e32 v2, vcc, 0x12b04000, v0
	s_nop 1
	v_addc_co_u32_e32 v3, vcc, 0, v1, vcc
	global_load_dwordx4 v[76:79], v[4:5], off
	global_load_dwordx4 v[72:75], v[4:5], off offset:1024
	global_load_dwordx4 v[68:71], v[4:5], off offset:2048
	global_load_dwordx4 v[64:67], v[4:5], off offset:3072
	v_add_co_u32_e32 v4, vcc, 0x12b05000, v0
	s_nop 1
	v_addc_co_u32_e32 v5, vcc, 0, v1, vcc
	global_load_dwordx4 v[60:63], v[2:3], off
	global_load_dwordx4 v[56:59], v[2:3], off offset:1024
	global_load_dwordx4 v[52:55], v[2:3], off offset:2048
	global_load_dwordx4 v[48:51], v[2:3], off offset:3072
	v_add_co_u32_e32 v2, vcc, 0x12b06000, v0
	s_nop 1
	v_addc_co_u32_e32 v3, vcc, 0, v1, vcc
	v_add_co_u32_e32 v0, vcc, 0x12b07000, v0
	s_nop 1
	v_addc_co_u32_e32 v1, vcc, 0, v1, vcc
	global_load_dwordx4 v[44:47], v[4:5], off
	global_load_dwordx4 v[40:43], v[4:5], off offset:1024
	global_load_dwordx4 v[36:39], v[4:5], off offset:2048
	global_load_dwordx4 v[32:35], v[4:5], off offset:3072
	global_load_dwordx4 v[28:31], v[2:3], off
	global_load_dwordx4 v[24:27], v[2:3], off offset:1024
	global_load_dwordx4 v[20:23], v[2:3], off offset:2048
	global_load_dwordx4 v[16:19], v[2:3], off offset:3072
	global_load_dwordx4 v[12:15], v[0:1], off
	global_load_dwordx4 v[8:11], v[0:1], off offset:1024
	global_load_dwordx4 v[4:7], v[0:1], off offset:2048
	global_load_dwordx4 v[0:3], v[0:1], off offset:3072
	s_waitcnt vmcnt(32)
	ds_write_b128 v194, v[196:199]
	ds_write_b128 v194, v[200:203] offset:8192
	s_waitcnt lgkmcnt(0)
	s_barrier
	s_waitcnt vmcnt(28)
	v_cvt_f32_f16_e32 v148, v134
	v_cvt_f32_f16_sdwa v149, v134 dst_sel:DWORD dst_unused:UNUSED_PAD src0_sel:WORD_1
	v_cvt_f32_f16_e32 v134, v132
	v_cvt_f32_f16_e32 v144, v135
	v_cvt_f32_f16_sdwa v145, v135 dst_sel:DWORD dst_unused:UNUSED_PAD src0_sel:WORD_1
	v_cvt_f32_f16_sdwa v135, v132 dst_sel:DWORD dst_unused:UNUSED_PAD src0_sel:WORD_1
	v_cvt_f32_f16_e32 v146, v133
	v_cvt_f32_f16_sdwa v147, v133 dst_sel:DWORD dst_unused:UNUSED_PAD src0_sel:WORD_1
	v_cvt_f32_f16_e32 v152, v136
	v_cvt_f32_f16_sdwa v153, v136 dst_sel:DWORD dst_unused:UNUSED_PAD src0_sel:WORD_1
	v_add_f32_e32 v136, 0, v134
	v_add_f32_e32 v136, v136, v135
	v_add_f32_e32 v136, v136, v146
	v_add_f32_e32 v136, v136, v147
	v_add_f32_e32 v136, v136, v148
	v_add_f32_e32 v136, v136, v149
	v_cvt_f32_f16_e32 v150, v137
	v_add_f32_e32 v136, v136, v144
	v_cvt_f32_f16_e32 v132, v139
	v_cvt_f32_f16_sdwa v133, v139 dst_sel:DWORD dst_unused:UNUSED_PAD src0_sel:WORD_1
	v_cvt_f32_f16_sdwa v151, v137 dst_sel:DWORD dst_unused:UNUSED_PAD src0_sel:WORD_1
	v_add_f32_e32 v139, v136, v145
	v_cvt_f32_f16_e32 v136, v138
	v_cvt_f32_f16_sdwa v137, v138 dst_sel:DWORD dst_unused:UNUSED_PAD src0_sel:WORD_1
	v_add_f32_e32 v138, v139, v152
	v_add_f32_e32 v138, v138, v153
	v_add_f32_e32 v138, v138, v150
	v_add_f32_e32 v138, v138, v151
	v_add_f32_e32 v138, v138, v136
	v_add_f32_e32 v138, v138, v137
	v_cvt_f32_f16_e32 v166, v140
	v_add_f32_e32 v138, v138, v132
	v_cvt_f32_f16_sdwa v167, v140 dst_sel:DWORD dst_unused:UNUSED_PAD src0_sel:WORD_1
	v_add_f32_e32 v154, v138, v133
	v_cvt_f32_f16_e32 v138, v141
	v_cvt_f32_f16_sdwa v139, v141 dst_sel:DWORD dst_unused:UNUSED_PAD src0_sel:WORD_1
	v_cvt_f32_f16_e32 v140, v142
	v_cvt_f32_f16_sdwa v141, v142 dst_sel:DWORD dst_unused:UNUSED_PAD src0_sel:WORD_1
	v_add_f32_e32 v142, v154, v166
	v_add_f32_e32 v142, v142, v167
	v_cvt_f32_f16_e32 v164, v143
	v_add_f32_e32 v142, v142, v138
	v_cvt_f32_f16_sdwa v165, v143 dst_sel:DWORD dst_unused:UNUSED_PAD src0_sel:WORD_1
	v_add_f32_e32 v142, v142, v139
	v_add_f32_e32 v142, v142, v140
	v_cvt_f32_f16_e32 v172, v112
	v_add_f32_e32 v142, v142, v141
	v_cvt_f32_f16_sdwa v173, v112 dst_sel:DWORD dst_unused:UNUSED_PAD src0_sel:WORD_1
	v_add_f32_e32 v142, v142, v164
	v_cvt_f32_f16_e32 v170, v113
	v_add_f32_e32 v142, v142, v165
	v_cvt_f32_f16_sdwa v171, v113 dst_sel:DWORD dst_unused:UNUSED_PAD src0_sel:WORD_1
	v_cvt_f32_f16_e32 v174, v114
	v_add_f32_e32 v112, v142, v172
	v_cvt_f32_f16_sdwa v175, v114 dst_sel:DWORD dst_unused:UNUSED_PAD src0_sel:WORD_1
	v_add_f32_e32 v112, v112, v173
	v_cvt_f32_f16_e32 v168, v115
	v_add_f32_e32 v112, v112, v170
	v_cvt_f32_f16_sdwa v169, v115 dst_sel:DWORD dst_unused:UNUSED_PAD src0_sel:WORD_1
	v_add_f32_e32 v112, v112, v171
	v_add_f32_e32 v112, v112, v174
	v_add_f32_e32 v112, v112, v175
	v_add_f32_e32 v112, v112, v168
	v_add_f32_e32 v112, v112, v169
	s_nop 1
	v_add_f32_dpp v112, v112, v112 quad_perm:[1,0,3,2] row_mask:0xf bank_mask:0xf bound_ctrl:1
	s_nop 1
	v_add_f32_dpp v112, v112, v112 quad_perm:[2,3,0,1] row_mask:0xf bank_mask:0xf bound_ctrl:1
	s_nop 1
	v_add_f32_dpp v112, v112, v112 row_half_mirror row_mask:0xf bank_mask:0xf bound_ctrl:1
	s_nop 1
	v_add_f32_dpp v112, v112, v112 row_mirror row_mask:0xf bank_mask:0xf bound_ctrl:1
	s_nop 0
	v_readlane_b32 s0, v112, 16
	v_readlane_b32 s7, v112, 48
	v_readlane_b32 s2, v112, 0
	v_readlane_b32 s3, v112, 32
	v_mov_b32_e32 v112, s0
	v_mov_b32_e32 v113, s7
	v_pk_add_f32 v[112:113], s[2:3], v[112:113]
	s_nop 0
	v_add_f32_e32 v112, v112, v113
	v_mul_f32_e32 v162, 0x3a000000, v112
	v_pk_add_f32 v[158:159], v[134:135], v[162:163] op_sel_hi:[1,0] neg_lo:[0,1] neg_hi:[0,1]
	v_pk_add_f32 v[112:113], v[146:147], v[162:163] op_sel_hi:[1,0] neg_lo:[0,1] neg_hi:[0,1]
	v_pk_mul_f32 v[176:177], v[158:159], v[158:159]
	v_pk_mul_f32 v[146:147], v[112:113], v[112:113]
	v_pk_add_f32 v[160:161], v[148:149], v[162:163] op_sel_hi:[1,0] neg_lo:[0,1] neg_hi:[0,1]
	v_pk_add_f32 v[156:157], v[144:145], v[162:163] op_sel_hi:[1,0] neg_lo:[0,1] neg_hi:[0,1]
	v_pk_add_f32 v[152:153], v[152:153], v[162:163] op_sel_hi:[1,0] neg_lo:[0,1] neg_hi:[0,1]
	v_pk_add_f32 v[148:149], v[150:151], v[162:163] op_sel_hi:[1,0] neg_lo:[0,1] neg_hi:[0,1]
	v_pk_add_f32 v[154:155], v[136:137], v[162:163] op_sel_hi:[1,0] neg_lo:[0,1] neg_hi:[0,1]
	v_pk_add_f32 v[150:151], v[132:133], v[162:163] op_sel_hi:[1,0] neg_lo:[0,1] neg_hi:[0,1]
	v_pk_add_f32 v[142:143], v[166:167], v[162:163] op_sel_hi:[1,0] neg_lo:[0,1] neg_hi:[0,1]
	v_pk_add_f32 v[138:139], v[138:139], v[162:163] op_sel_hi:[1,0] neg_lo:[0,1] neg_hi:[0,1]
	v_pk_add_f32 v[144:145], v[140:141], v[162:163] op_sel_hi:[1,0] neg_lo:[0,1] neg_hi:[0,1]
	v_pk_add_f32 v[140:141], v[164:165], v[162:163] op_sel_hi:[1,0] neg_lo:[0,1] neg_hi:[0,1]
	v_pk_add_f32 v[132:133], v[172:173], v[162:163] op_sel_hi:[1,0] neg_lo:[0,1] neg_hi:[0,1]
	v_pk_add_f32 v[114:115], v[170:171], v[162:163] op_sel_hi:[1,0] neg_lo:[0,1] neg_hi:[0,1]
	v_pk_add_f32 v[136:137], v[174:175], v[162:163] op_sel_hi:[1,0] neg_lo:[0,1] neg_hi:[0,1]
	v_pk_add_f32 v[134:135], v[168:169], v[162:163] op_sel_hi:[1,0] neg_lo:[0,1] neg_hi:[0,1]
	v_add_f32_e32 v163, v176, v177
	v_add_f32_e32 v146, v146, v163
	v_pk_mul_f32 v[178:179], v[160:161], v[160:161]
	v_add_f32_e32 v146, v147, v146
	v_add_f32_e32 v146, v178, v146
	v_pk_mul_f32 v[180:181], v[156:157], v[156:157]
	v_add_f32_e32 v146, v179, v146
	v_add_f32_e32 v146, v180, v146
	v_pk_mul_f32 v[182:183], v[152:153], v[152:153]
	v_add_f32_e32 v146, v181, v146
	v_add_f32_e32 v146, v182, v146
	v_pk_mul_f32 v[184:185], v[148:149], v[148:149]
	v_add_f32_e32 v146, v183, v146
	v_add_f32_e32 v146, v184, v146
	v_pk_mul_f32 v[186:187], v[154:155], v[154:155]
	v_add_f32_e32 v146, v185, v146
	v_add_f32_e32 v146, v186, v146
	v_pk_mul_f32 v[188:189], v[150:151], v[150:151]
	v_add_f32_e32 v146, v187, v146
	v_add_f32_e32 v146, v188, v146
	v_pk_mul_f32 v[166:167], v[142:143], v[142:143]
	v_add_f32_e32 v146, v189, v146
	v_add_f32_e32 v146, v166, v146
	v_pk_mul_f32 v[190:191], v[138:139], v[138:139]
	v_add_f32_e32 v146, v167, v146
	v_add_f32_e32 v146, v190, v146
	v_pk_mul_f32 v[192:193], v[144:145], v[144:145]
	v_add_f32_e32 v146, v191, v146
	v_add_f32_e32 v146, v192, v146
	v_pk_mul_f32 v[164:165], v[140:141], v[140:141]
	v_add_f32_e32 v146, v193, v146
	v_add_f32_e32 v146, v164, v146
	v_pk_mul_f32 v[172:173], v[132:133], v[132:133]
	v_add_f32_e32 v146, v165, v146
	v_add_f32_e32 v146, v172, v146
	v_pk_mul_f32 v[170:171], v[114:115], v[114:115]
	v_add_f32_e32 v146, v173, v146
	v_add_f32_e32 v146, v170, v146
	v_pk_mul_f32 v[174:175], v[136:137], v[136:137]
	v_add_f32_e32 v146, v171, v146
	v_add_f32_e32 v146, v174, v146
	v_pk_mul_f32 v[168:169], v[134:135], v[134:135]
	v_add_f32_e32 v146, v175, v146
	v_add_f32_e32 v146, v168, v146
	v_add_f32_e32 v146, v169, v146
	s_nop 1
	v_add_f32_dpp v146, v146, v146 quad_perm:[1,0,3,2] row_mask:0xf bank_mask:0xf bound_ctrl:1
	s_nop 1
	v_add_f32_dpp v146, v146, v146 quad_perm:[2,3,0,1] row_mask:0xf bank_mask:0xf bound_ctrl:1
	s_nop 1
	v_add_f32_dpp v146, v146, v146 row_half_mirror row_mask:0xf bank_mask:0xf bound_ctrl:1
	s_nop 1
	v_add_f32_dpp v146, v146, v146 row_mirror row_mask:0xf bank_mask:0xf bound_ctrl:1
	s_nop 0
	v_readlane_b32 s2, v146, 16
	v_readlane_b32 s0, v146, 0
	s_nop 0
	v_mov_b32_e32 v147, s2
	v_readlane_b32 s2, v146, 48
	v_add_f32_e32 v147, s0, v147
	v_readlane_b32 s0, v146, 32
	v_mov_b32_e32 v146, s2
	s_nop 0
	v_add_f32_e32 v146, s0, v146
	v_add_f32_e32 v146, v147, v146
	v_fmamk_f32 v146, v146, 0x3a000000, v245
	v_mul_f32_e32 v147, 0x4f800000, v146
	v_cmp_gt_f32_e32 vcc, s87, v146
	s_nop 1
	v_cndmask_b32_e32 v146, v146, v147, vcc
	v_sqrt_f32_e32 v147, v146
	s_nop 0
	v_add_u32_e32 v163, -1, v147
	v_fma_f32 v164, -v163, v147, v146
	v_cmp_ge_f32_e64 s[40:41], 0, v164
	v_add_u32_e32 v164, 1, v147
	s_nop 0
	v_cndmask_b32_e64 v163, v147, v163, s[40:41]
	v_fma_f32 v147, -v164, v147, v146
	v_cmp_lt_f32_e64 s[40:41], 0, v147
	s_nop 1
	v_cndmask_b32_e64 v147, v163, v164, s[40:41]
	v_mul_f32_e32 v163, 0x37800000, v147
	v_cndmask_b32_e32 v147, v147, v163, vcc
	v_cmp_class_f32_e32 vcc, v146, v243
	s_nop 1
	v_cndmask_b32_e32 v146, v147, v146, vcc
	v_div_scale_f32 v147, s[2:3], v146, v146, 1.0
	v_rcp_f32_e32 v163, v147
	s_nop 0
	v_fma_f32 v164, -v147, v163, 1.0
	v_fmac_f32_e32 v163, v164, v163
	v_div_scale_f32 v164, vcc, 1.0, v146, 1.0
	v_mul_f32_e32 v165, v164, v163
	v_fma_f32 v166, -v147, v165, v164
	v_fmac_f32_e32 v165, v166, v163
	v_fma_f32 v147, -v147, v165, v164
	v_div_fmas_f32 v147, v147, v163, v165
	v_div_fixup_f32 v146, v147, v146, 1.0
	s_and_saveexec_b64 s[8:9], s[42:43]
	s_cbranch_execz .LBB0_1964
	s_ashr_i32 s45, s44, 31
	s_lshl_b64 s[2:3], s[44:45], 2
	s_add_u32 s2, s12, s2
	v_mov_b32_e32 v163, v146
	s_addc_u32 s3, s13, s3
	global_store_dwordx2 v225, v[162:163], s[2:3]

.Lmy_g3_own:
	s_cmp_eq_u32 s100, 32
	s_cbranch_scc1 .Lmy_g3_all
	s_branch .Lmy_gdone_3

.Lmy_lnmap_b:
	s_lshl_b32 s2, s99, 3
	s_add_i32 s2, s0, s2
	s_mov_b64 s[12:13], s[96:97]
	s_mov_b64 s[16:17], s[96:97]
	s_mov_b64 s[20:21], s[96:97]
	s_mov_b64 s[18:19], s[96:97]
	s_cmpk_gt_i32 s2, 0x7ff
	s_cbranch_scc1 .LBB0_2327
	s_load_dwordx2 s[20:21], s[20:21], 0x110
	s_nop 0
	s_load_dwordx2 s[8:9], s[8:9], 0x110
	s_nop 0
	s_load_dwordx2 s[22:23], s[12:13], 0x10
	s_nop 0
	s_load_dwordx2 s[16:17], s[16:17], 0x18
	s_nop 0
	s_load_dwordx2 s[18:19], s[18:19], 0x110
	s_waitcnt lgkmcnt(0)
	s_add_u32 s12, s20, 0x920000
	s_addc_u32 s13, s21, 0
	s_lshl_b32 s3, s48, 12
	s_or_b32 s10, s3, 0x800
	s_lshl_b64 s[20:21], s[10:11], 2
	s_add_u32 s16, s16, s20
	s_addc_u32 s17, s17, s21
	v_lshlrev_b32_e32 v2, 3, v0
	s_add_u32 s20, s22, s20
	v_ashrrev_i32_e32 v3, 31, v2
	s_addc_u32 s21, s23, s21
	s_lshl_b32 s36, s2, 3
	v_lshlrev_b64 v[4:5], 2, v[2:3]
	s_mov_b64 s[2:3], 0x1000
	v_lshl_add_u64 v[6:7], v[4:5], 0, s[2:3]
	s_mov_b64 s[2:3], 0x1800
	v_ashrrev_i32_e32 v1, 31, v0
	s_lshl_b32 s98, s80, 10
	v_lshl_add_u32 v194, v0, 4, s98
	global_load_dwordx4 v[196:199], v194, s[20:21]
	global_load_dwordx4 v[200:203], v194, s[16:17]
	v_lshlrev_b32_e32 v195, 5, v0
	v_lshl_add_u64 v[116:117], s[20:21], 0, v[4:5]
	v_lshl_add_u64 v[118:119], s[16:17], 0, v[4:5]
	v_lshl_add_u64 v[4:5], v[4:5], 0, s[2:3]
	s_lshl_b32 s0, s0, 4
	s_ashr_i32 s37, s36, 31
	v_cmp_eq_u32_e64 s[40:41], 0, v0
	v_lshl_add_u64 v[120:121], s[20:21], 0, v[6:7]
	v_lshl_add_u64 v[122:123], s[16:17], 0, v[6:7]
	v_lshl_add_u64 v[124:125], s[20:21], 0, v[4:5]
	v_lshl_add_u64 v[126:127], s[16:17], 0, v[4:5]
	s_lshl_b32 s44, s99, 7
	s_add_i32 s44, s44, s0
	s_lshl_b64 s[46:47], s[36:37], 12
	v_lshl_add_u64 v[128:129], v[2:3], 1, s[18:19]
	v_lshl_add_u64 v[130:131], v[0:1], 4, s[8:9]
	s_branch .LBB0_2311

.LBB0_2311:
	s_nop 0
	v_lshl_add_u64 v[0:1], v[130:131], 0, s[46:47]
	v_add_co_u32_e32 v2, vcc, 0x12b00000, v0
	s_nop 1
	v_addc_co_u32_e32 v3, vcc, 0, v1, vcc
	global_load_dwordx4 v[132:135], v[2:3], off
	global_load_dwordx4 v[136:139], v[2:3], off offset:1024
	global_load_dwordx4 v[140:143], v[2:3], off offset:2048
	global_load_dwordx4 v[112:115], v[2:3], off offset:3072
	v_add_co_u32_e32 v4, vcc, 0x12b01000, v0
	s_nop 1
	v_addc_co_u32_e32 v5, vcc, 0, v1, vcc
	v_add_co_u32_e32 v2, vcc, 0x12b02000, v0
	s_nop 1
	v_addc_co_u32_e32 v3, vcc, 0, v1, vcc
	global_load_dwordx4 v[108:111], v[4:5], off
	global_load_dwordx4 v[104:107], v[4:5], off offset:1024
	global_load_dwordx4 v[100:103], v[4:5], off offset:2048
	global_load_dwordx4 v[96:99], v[4:5], off offset:3072
	v_add_co_u32_e32 v4, vcc, 0x12b03000, v0
	s_nop 1
	v_addc_co_u32_e32 v5, vcc, 0, v1, vcc
	global_load_dwordx4 v[92:95], v[2:3], off
	global_load_dwordx4 v[88:91], v[2:3], off offset:1024
	global_load_dwordx4 v[84:87], v[2:3], off offset:2048
	global_load_dwordx4 v[80:83], v[2:3], off offset:3072
	v_add_co_u32_e32 v2, vcc, 0x12b04000, v0
	s_nop 1
	v_addc_co_u32_e32 v3, vcc, 0, v1, vcc
	global_load_dwordx4 v[76:79], v[4:5], off
	global_load_dwordx4 v[72:75], v[4:5], off offset:1024
	global_load_dwordx4 v[68:71], v[4:5], off offset:2048
	global_load_dwordx4 v[64:67], v[4:5], off offset:3072
	v_add_co_u32_e32 v4, vcc, 0x12b05000, v0
	s_nop 1
	v_addc_co_u32_e32 v5, vcc, 0, v1, vcc
	global_load_dwordx4 v[60:63], v[2:3], off
	global_load_dwordx4 v[56:59], v[2:3], off offset:1024
	global_load_dwordx4 v[52:55], v[2:3], off offset:2048
	global_load_dwordx4 v[48:51], v[2:3], off offset:3072
	v_add_co_u32_e32 v2, vcc, 0x12b06000, v0
	s_nop 1
	v_addc_co_u32_e32 v3, vcc, 0, v1, vcc
	v_add_co_u32_e32 v0, vcc, 0x12b07000, v0
	s_nop 1
	v_addc_co_u32_e32 v1, vcc, 0, v1, vcc
	global_load_dwordx4 v[44:47], v[4:5], off
	global_load_dwordx4 v[40:43], v[4:5], off offset:1024
	global_load_dwordx4 v[36:39], v[4:5], off offset:2048
	global_load_dwordx4 v[32:35], v[4:5], off offset:3072
	global_load_dwordx4 v[28:31], v[2:3], off
	global_load_dwordx4 v[24:27], v[2:3], off offset:1024
	global_load_dwordx4 v[20:23], v[2:3], off offset:2048
	global_load_dwordx4 v[16:19], v[2:3], off offset:3072
	global_load_dwordx4 v[12:15], v[0:1], off
	global_load_dwordx4 v[8:11], v[0:1], off offset:1024
	global_load_dwordx4 v[4:7], v[0:1], off offset:2048
	global_load_dwordx4 v[0:3], v[0:1], off offset:3072
	s_waitcnt vmcnt(32)
	ds_write_b128 v194, v[196:199]
	ds_write_b128 v194, v[200:203] offset:8192
	s_waitcnt lgkmcnt(0)
	s_barrier
	s_waitcnt vmcnt(28)
	v_cvt_f32_f16_e32 v148, v134
	v_cvt_f32_f16_sdwa v149, v134 dst_sel:DWORD dst_unused:UNUSED_PAD src0_sel:WORD_1
	v_cvt_f32_f16_e32 v134, v132
	v_cvt_f32_f16_e32 v144, v135
	v_cvt_f32_f16_sdwa v145, v135 dst_sel:DWORD dst_unused:UNUSED_PAD src0_sel:WORD_1
	v_cvt_f32_f16_sdwa v135, v132 dst_sel:DWORD dst_unused:UNUSED_PAD src0_sel:WORD_1
	v_cvt_f32_f16_e32 v146, v133
	v_cvt_f32_f16_sdwa v147, v133 dst_sel:DWORD dst_unused:UNUSED_PAD src0_sel:WORD_1
	v_cvt_f32_f16_e32 v152, v136
	v_cvt_f32_f16_sdwa v153, v136 dst_sel:DWORD dst_unused:UNUSED_PAD src0_sel:WORD_1
	v_add_f32_e32 v136, 0, v134
	v_add_f32_e32 v136, v136, v135
	v_add_f32_e32 v136, v136, v146
	v_add_f32_e32 v136, v136, v147
	v_add_f32_e32 v136, v136, v148
	v_add_f32_e32 v136, v136, v149
	v_cvt_f32_f16_e32 v150, v137
	v_add_f32_e32 v136, v136, v144
	v_cvt_f32_f16_e32 v132, v139
	v_cvt_f32_f16_sdwa v133, v139 dst_sel:DWORD dst_unused:UNUSED_PAD src0_sel:WORD_1
	v_cvt_f32_f16_sdwa v151, v137 dst_sel:DWORD dst_unused:UNUSED_PAD src0_sel:WORD_1
	v_add_f32_e32 v139, v136, v145
	v_cvt_f32_f16_e32 v136, v138
	v_cvt_f32_f16_sdwa v137, v138 dst_sel:DWORD dst_unused:UNUSED_PAD src0_sel:WORD_1
	v_add_f32_e32 v138, v139, v152
	v_add_f32_e32 v138, v138, v153
	v_add_f32_e32 v138, v138, v150
	v_add_f32_e32 v138, v138, v151
	v_add_f32_e32 v138, v138, v136
	v_add_f32_e32 v138, v138, v137
	v_cvt_f32_f16_e32 v166, v140
	v_add_f32_e32 v138, v138, v132
	v_cvt_f32_f16_sdwa v167, v140 dst_sel:DWORD dst_unused:UNUSED_PAD src0_sel:WORD_1
	v_add_f32_e32 v154, v138, v133
	v_cvt_f32_f16_e32 v138, v141
	v_cvt_f32_f16_sdwa v139, v141 dst_sel:DWORD dst_unused:UNUSED_PAD src0_sel:WORD_1
	v_cvt_f32_f16_e32 v140, v142
	v_cvt_f32_f16_sdwa v141, v142 dst_sel:DWORD dst_unused:UNUSED_PAD src0_sel:WORD_1
	v_add_f32_e32 v142, v154, v166
	v_add_f32_e32 v142, v142, v167
	v_cvt_f32_f16_e32 v164, v143
	v_add_f32_e32 v142, v142, v138
	v_cvt_f32_f16_sdwa v165, v143 dst_sel:DWORD dst_unused:UNUSED_PAD src0_sel:WORD_1
	v_add_f32_e32 v142, v142, v139
	v_add_f32_e32 v142, v142, v140
	v_cvt_f32_f16_e32 v172, v112
	v_add_f32_e32 v142, v142, v141
	v_cvt_f32_f16_sdwa v173, v112 dst_sel:DWORD dst_unused:UNUSED_PAD src0_sel:WORD_1
	v_add_f32_e32 v142, v142, v164
	v_cvt_f32_f16_e32 v170, v113
	v_add_f32_e32 v142, v142, v165
	v_cvt_f32_f16_sdwa v171, v113 dst_sel:DWORD dst_unused:UNUSED_PAD src0_sel:WORD_1
	v_cvt_f32_f16_e32 v174, v114
	v_add_f32_e32 v112, v142, v172
	v_cvt_f32_f16_sdwa v175, v114 dst_sel:DWORD dst_unused:UNUSED_PAD src0_sel:WORD_1
	v_add_f32_e32 v112, v112, v173
	v_cvt_f32_f16_e32 v168, v115
	v_add_f32_e32 v112, v112, v170
	v_cvt_f32_f16_sdwa v169, v115 dst_sel:DWORD dst_unused:UNUSED_PAD src0_sel:WORD_1
	v_add_f32_e32 v112, v112, v171
	v_add_f32_e32 v112, v112, v174
	v_add_f32_e32 v112, v112, v175
	v_add_f32_e32 v112, v112, v168
	v_add_f32_e32 v112, v112, v169
	s_nop 1
	v_add_f32_dpp v112, v112, v112 quad_perm:[1,0,3,2] row_mask:0xf bank_mask:0xf bound_ctrl:1
	s_nop 1
	v_add_f32_dpp v112, v112, v112 quad_perm:[2,3,0,1] row_mask:0xf bank_mask:0xf bound_ctrl:1
	s_nop 1
	v_add_f32_dpp v112, v112, v112 row_half_mirror row_mask:0xf bank_mask:0xf bound_ctrl:1
	s_nop 1
	v_add_f32_dpp v112, v112, v112 row_mirror row_mask:0xf bank_mask:0xf bound_ctrl:1
	s_nop 0
	v_readlane_b32 s0, v112, 16
	v_readlane_b32 s7, v112, 48
	v_readlane_b32 s2, v112, 0
	v_readlane_b32 s3, v112, 32
	v_mov_b32_e32 v112, s0
	v_mov_b32_e32 v113, s7
	v_pk_add_f32 v[112:113], s[2:3], v[112:113]
	s_nop 0
	v_add_f32_e32 v112, v112, v113
	v_mul_f32_e32 v162, 0x3a000000, v112
	v_pk_add_f32 v[158:159], v[134:135], v[162:163] op_sel_hi:[1,0] neg_lo:[0,1] neg_hi:[0,1]
	v_pk_add_f32 v[112:113], v[146:147], v[162:163] op_sel_hi:[1,0] neg_lo:[0,1] neg_hi:[0,1]
	v_pk_mul_f32 v[176:177], v[158:159], v[158:159]
	v_pk_mul_f32 v[146:147], v[112:113], v[112:113]
	v_pk_add_f32 v[160:161], v[148:149], v[162:163] op_sel_hi:[1,0] neg_lo:[0,1] neg_hi:[0,1]
	v_pk_add_f32 v[156:157], v[144:145], v[162:163] op_sel_hi:[1,0] neg_lo:[0,1] neg_hi:[0,1]
	v_pk_add_f32 v[152:153], v[152:153], v[162:163] op_sel_hi:[1,0] neg_lo:[0,1] neg_hi:[0,1]
	v_pk_add_f32 v[148:149], v[150:151], v[162:163] op_sel_hi:[1,0] neg_lo:[0,1] neg_hi:[0,1]
	v_pk_add_f32 v[154:155], v[136:137], v[162:163] op_sel_hi:[1,0] neg_lo:[0,1] neg_hi:[0,1]
	v_pk_add_f32 v[150:151], v[132:133], v[162:163] op_sel_hi:[1,0] neg_lo:[0,1] neg_hi:[0,1]
	v_pk_add_f32 v[142:143], v[166:167], v[162:163] op_sel_hi:[1,0] neg_lo:[0,1] neg_hi:[0,1]
	v_pk_add_f32 v[138:139], v[138:139], v[162:163] op_sel_hi:[1,0] neg_lo:[0,1] neg_hi:[0,1]
	v_pk_add_f32 v[144:145], v[140:141], v[162:163] op_sel_hi:[1,0] neg_lo:[0,1] neg_hi:[0,1]
	v_pk_add_f32 v[140:141], v[164:165], v[162:163] op_sel_hi:[1,0] neg_lo:[0,1] neg_hi:[0,1]
	v_pk_add_f32 v[132:133], v[172:173], v[162:163] op_sel_hi:[1,0] neg_lo:[0,1] neg_hi:[0,1]
	v_pk_add_f32 v[114:115], v[170:171], v[162:163] op_sel_hi:[1,0] neg_lo:[0,1] neg_hi:[0,1]
	v_pk_add_f32 v[136:137], v[174:175], v[162:163] op_sel_hi:[1,0] neg_lo:[0,1] neg_hi:[0,1]
	v_pk_add_f32 v[134:135], v[168:169], v[162:163] op_sel_hi:[1,0] neg_lo:[0,1] neg_hi:[0,1]
	v_add_f32_e32 v163, v176, v177
	v_add_f32_e32 v146, v146, v163
	v_pk_mul_f32 v[178:179], v[160:161], v[160:161]
	v_add_f32_e32 v146, v147, v146
	v_add_f32_e32 v146, v178, v146
	v_pk_mul_f32 v[180:181], v[156:157], v[156:157]
	v_add_f32_e32 v146, v179, v146
	v_add_f32_e32 v146, v180, v146
	v_pk_mul_f32 v[182:183], v[152:153], v[152:153]
	v_add_f32_e32 v146, v181, v146
	v_add_f32_e32 v146, v182, v146
	v_pk_mul_f32 v[184:185], v[148:149], v[148:149]
	v_add_f32_e32 v146, v183, v146
	v_add_f32_e32 v146, v184, v146
	v_pk_mul_f32 v[186:187], v[154:155], v[154:155]
	v_add_f32_e32 v146, v185, v146
	v_add_f32_e32 v146, v186, v146
	v_pk_mul_f32 v[188:189], v[150:151], v[150:151]
	v_add_f32_e32 v146, v187, v146
	v_add_f32_e32 v146, v188, v146
	v_pk_mul_f32 v[166:167], v[142:143], v[142:143]
	v_add_f32_e32 v146, v189, v146
	v_add_f32_e32 v146, v166, v146
	v_pk_mul_f32 v[190:191], v[138:139], v[138:139]
	v_add_f32_e32 v146, v167, v146
	v_add_f32_e32 v146, v190, v146
	v_pk_mul_f32 v[192:193], v[144:145], v[144:145]
	v_add_f32_e32 v146, v191, v146
	v_add_f32_e32 v146, v192, v146
	v_pk_mul_f32 v[164:165], v[140:141], v[140:141]
	v_add_f32_e32 v146, v193, v146
	v_add_f32_e32 v146, v164, v146
	v_pk_mul_f32 v[172:173], v[132:133], v[132:133]
	v_add_f32_e32 v146, v165, v146
	v_add_f32_e32 v146, v172, v146
	v_pk_mul_f32 v[170:171], v[114:115], v[114:115]
	v_add_f32_e32 v146, v173, v146
	v_add_f32_e32 v146, v170, v146
	v_pk_mul_f32 v[174:175], v[136:137], v[136:137]
	v_add_f32_e32 v146, v171, v146
	v_add_f32_e32 v146, v174, v146
	v_pk_mul_f32 v[168:169], v[134:135], v[134:135]
	v_add_f32_e32 v146, v175, v146
	v_add_f32_e32 v146, v168, v146
	v_add_f32_e32 v146, v169, v146
	s_nop 1
	v_add_f32_dpp v146, v146, v146 quad_perm:[1,0,3,2] row_mask:0xf bank_mask:0xf bound_ctrl:1
	s_nop 1
	v_add_f32_dpp v146, v146, v146 quad_perm:[2,3,0,1] row_mask:0xf bank_mask:0xf bound_ctrl:1
	s_nop 1
	v_add_f32_dpp v146, v146, v146 row_half_mirror row_mask:0xf bank_mask:0xf bound_ctrl:1
	s_nop 1
	v_add_f32_dpp v146, v146, v146 row_mirror row_mask:0xf bank_mask:0xf bound_ctrl:1
	s_nop 0
	v_readlane_b32 s2, v146, 16
	v_readlane_b32 s0, v146, 0
	s_nop 0
	v_mov_b32_e32 v147, s2
	v_readlane_b32 s2, v146, 48
	v_add_f32_e32 v147, s0, v147
	v_readlane_b32 s0, v146, 32
	v_mov_b32_e32 v146, s2
	s_nop 0
	v_add_f32_e32 v146, s0, v146
	v_add_f32_e32 v146, v147, v146
	v_fmamk_f32 v146, v146, 0x3a000000, v245
	v_mul_f32_e32 v147, 0x4f800000, v146
	v_cmp_gt_f32_e32 vcc, s87, v146
	s_nop 1
	v_cndmask_b32_e32 v146, v146, v147, vcc
	v_sqrt_f32_e32 v147, v146
	s_nop 0
	v_add_u32_e32 v163, -1, v147
	v_fma_f32 v164, -v163, v147, v146
	v_cmp_ge_f32_e64 s[42:43], 0, v164
	v_add_u32_e32 v164, 1, v147
	s_nop 0
	v_cndmask_b32_e64 v163, v147, v163, s[42:43]
	v_fma_f32 v147, -v164, v147, v146
	v_cmp_lt_f32_e64 s[42:43], 0, v147
	s_nop 1
	v_cndmask_b32_e64 v147, v163, v164, s[42:43]
	v_mul_f32_e32 v163, 0x37800000, v147
	v_cndmask_b32_e32 v147, v147, v163, vcc
	v_cmp_class_f32_e32 vcc, v146, v243
	s_nop 1
	v_cndmask_b32_e32 v146, v147, v146, vcc
	v_div_scale_f32 v147, s[2:3], v146, v146, 1.0
	v_rcp_f32_e32 v163, v147
	s_nop 0
	v_fma_f32 v164, -v147, v163, 1.0
	v_fmac_f32_e32 v163, v164, v163
	v_div_scale_f32 v164, vcc, 1.0, v146, 1.0
	v_mul_f32_e32 v165, v164, v163
	v_fma_f32 v166, -v147, v165, v164
	v_fmac_f32_e32 v165, v166, v163
	v_fma_f32 v147, -v147, v165, v164
	v_div_fmas_f32 v147, v147, v163, v165
	v_div_fixup_f32 v146, v147, v146, 1.0
	s_and_saveexec_b64 s[8:9], s[40:41]
	s_cbranch_execz .LBB0_2313
	s_ashr_i32 s45, s44, 31
	s_lshl_b64 s[2:3], s[44:45], 2
	s_add_u32 s2, s12, s2
	v_mov_b32_e32 v163, v146
	s_addc_u32 s3, s13, s3
	global_store_dwordx2 v225, v[162:163], s[2:3]
